# hgrn_a: unit output stores deferred and spread through the next unit's VALU stages (data parked in registers)
# baseline (speedup 1.0000x reference)
; __device__ __forceinline__ void hgrn_a_load(Ctx& X, int u, RawA& R) {
;     const int hd = u & 7, c = u >> 3, t0 = c * 64, seg = X.tid >> 7, k = X.tid & 127;
;     const bf16_t* HLF = (const bf16_t*)(X.ws + WS_PROJ) + 4 * TSZ; const bf16_t* HV = (const bf16_t*)(X.ws + WS_PROJ) + 5 * TSZ;
; #pragma unroll
;     for (int i = 0; i < 16; ++i) { const size_t off = (size_t)(t0 + 16 * seg + i) * 1024 + hd * 128 + k; R.lf[i] = HLF[off]; R.vv[i] = HV[off]; }
; }
; __global__ void __launch_bounds__(512, 2) fwd_mega(Args a) {
;     ...
;     if (IN(3)) {
;         {
;             RawA cur; hgrn_a_load(X, blockIdx.x, cur);
;             for (int u = blockIdx.x; u < 2048; u += X.G) { RawA nxt = cur; if (u + X.G < 2048) hgrn_a_load(X, u + X.G, nxt); hgrn_a_compute(X, u, cur); cur = nxt; }
.LBB0_463:
	s_cmp_lt_i32 s92, 4
	s_cselect_b64 s[2:3], -1, 0
	s_and_b64 s[34:35], s[2:3], s[0:1]
	s_andn2_b64 vcc, exec, s[34:35]
	s_cbranch_vccnz .LBB0_616
	s_mov_b32 s98, 0
	v_readlane_b32 s0, v245, 0
	s_cmpk_gt_i32 s0, 0x7ff
	v_readlane_b32 s1, v245, 1
	s_cbranch_scc1 .LBB0_471
	s_add_u32 s10, s90, 0x13700000
	s_addc_u32 s11, s91, 0
	s_add_u32 s12, s90, 0x15700000
	v_lshrrev_b32_e32 v0, 3, v209
	s_addc_u32 s13, s91, 0
	v_and_b32_e32 v41, 0x70, v0
	s_and_b32 s0, s54, 0xffffffc0
	v_readlane_b32 s20, v245, 0
	v_add_u32_e32 v20, s0, v41
	s_lshl_b32 s0, s20, 7
	v_and_b32_e32 v40, 0x7f, v209
	v_or_b32_e32 v0, 15, v20
	s_and_b32 s0, s0, 0x380
	v_ashrrev_i32_e32 v1, 31, v0
	v_or_b32_e32 v2, s0, v40
	v_lshlrev_b64 v[0:1], 11, v[0:1]
	v_lshlrev_b32_e32 v44, 1, v2
	v_or_b32_e32 v0, v0, v44
	v_lshl_add_u64 v[4:5], s[12:13], 0, v[0:1]
	v_lshl_add_u64 v[8:9], s[10:11], 0, v[0:1]
	v_or_b32_e32 v0, 14, v20
	v_ashrrev_i32_e32 v1, 31, v0
	v_lshlrev_b64 v[0:1], 11, v[0:1]
	v_or_b32_e32 v0, v0, v44
	v_lshl_add_u64 v[12:13], s[12:13], 0, v[0:1]
	v_lshl_add_u64 v[14:15], s[10:11], 0, v[0:1]
	v_or_b32_e32 v0, 13, v20
	v_ashrrev_i32_e32 v1, 31, v0
	v_lshlrev_b64 v[0:1], 11, v[0:1]
	v_or_b32_e32 v0, v0, v44
	v_lshl_add_u64 v[16:17], s[12:13], 0, v[0:1]
	v_lshl_add_u64 v[18:19], s[10:11], 0, v[0:1]
	v_or_b32_e32 v0, 12, v20
	v_ashrrev_i32_e32 v1, 31, v0
	v_lshlrev_b64 v[0:1], 11, v[0:1]
	v_or_b32_e32 v0, v0, v44
	v_lshl_add_u64 v[22:23], s[12:13], 0, v[0:1]
	v_lshl_add_u64 v[24:25], s[10:11], 0, v[0:1]
	global_load_ushort v2, v[4:5], off
	global_load_ushort v6, v[8:9], off
	global_load_ushort v3, v[12:13], off
	global_load_ushort v7, v[14:15], off
	global_load_ushort v1, v[16:17], off
	global_load_ushort v10, v[18:19], off
	global_load_ushort v0, v[22:23], off
	global_load_ushort v11, v[24:25], off
	v_or_b32_e32 v4, 11, v20
	v_ashrrev_i32_e32 v5, 31, v4
	v_lshlrev_b64 v[4:5], 11, v[4:5]
	v_or_b32_e32 v4, v4, v44
	v_lshl_add_u64 v[12:13], s[12:13], 0, v[4:5]
	v_lshl_add_u64 v[22:23], s[10:11], 0, v[4:5]
	v_or_b32_e32 v4, 10, v20
	v_ashrrev_i32_e32 v5, 31, v4
	v_lshlrev_b64 v[4:5], 11, v[4:5]
	v_or_b32_e32 v4, v4, v44
	v_lshl_add_u64 v[24:25], s[12:13], 0, v[4:5]
	v_lshl_add_u64 v[26:27], s[10:11], 0, v[4:5]
	v_or_b32_e32 v4, 9, v20
	v_ashrrev_i32_e32 v5, 31, v4
	v_lshlrev_b64 v[4:5], 11, v[4:5]
	v_or_b32_e32 v4, v4, v44
	v_lshl_add_u64 v[28:29], s[12:13], 0, v[4:5]
	v_lshl_add_u64 v[30:31], s[10:11], 0, v[4:5]
	v_or_b32_e32 v4, 8, v20
	v_ashrrev_i32_e32 v5, 31, v4
	v_lshlrev_b64 v[4:5], 11, v[4:5]
	v_or_b32_e32 v4, v4, v44
	v_lshl_add_u64 v[32:33], s[12:13], 0, v[4:5]
	v_lshl_add_u64 v[34:35], s[10:11], 0, v[4:5]
	global_load_ushort v4, v[12:13], off
	global_load_ushort v14, v[22:23], off
	global_load_ushort v5, v[24:25], off
	global_load_ushort v15, v[26:27], off
	global_load_ushort v8, v[28:29], off
	global_load_ushort v16, v[30:31], off
	global_load_ushort v9, v[32:33], off
	global_load_ushort v19, v[34:35], off
	v_or_b32_e32 v12, 7, v20
	v_ashrrev_i32_e32 v13, 31, v12
	v_lshlrev_b64 v[12:13], 11, v[12:13]
	v_or_b32_e32 v12, v12, v44
	v_lshl_add_u64 v[26:27], s[12:13], 0, v[12:13]
	v_lshl_add_u64 v[28:29], s[10:11], 0, v[12:13]
	v_or_b32_e32 v12, 6, v20
	v_ashrrev_i32_e32 v13, 31, v12
	v_lshlrev_b64 v[12:13], 11, v[12:13]
	v_or_b32_e32 v12, v12, v44
	v_lshl_add_u64 v[30:31], s[12:13], 0, v[12:13]
	v_lshl_add_u64 v[32:33], s[10:11], 0, v[12:13]
	v_or_b32_e32 v12, 5, v20
	v_ashrrev_i32_e32 v13, 31, v12
	v_lshlrev_b64 v[12:13], 11, v[12:13]
	v_or_b32_e32 v12, v12, v44
	v_lshl_add_u64 v[34:35], s[12:13], 0, v[12:13]
	v_lshl_add_u64 v[36:37], s[10:11], 0, v[12:13]
	v_or_b32_e32 v12, 4, v20
	v_ashrrev_i32_e32 v13, 31, v12
	v_lshlrev_b64 v[12:13], 11, v[12:13]
	v_or_b32_e32 v12, v12, v44
	v_lshl_add_u64 v[38:39], s[12:13], 0, v[12:13]
	v_lshl_add_u64 v[42:43], s[10:11], 0, v[12:13]
	global_load_ushort v12, v[26:27], off
	global_load_ushort v22, v[28:29], off
	global_load_ushort v13, v[30:31], off
	global_load_ushort v23, v[32:33], off
	global_load_ushort v17, v[34:35], off
	global_load_ushort v24, v[36:37], off
	global_load_ushort v18, v[38:39], off
	global_load_ushort v25, v[42:43], off
	v_or_b32_e32 v26, 3, v20
	v_ashrrev_i32_e32 v27, 31, v26
	v_lshlrev_b64 v[26:27], 11, v[26:27]
	v_or_b32_e32 v26, v26, v44
	v_lshl_add_u64 v[28:29], s[12:13], 0, v[26:27]
	v_lshl_add_u64 v[32:33], s[10:11], 0, v[26:27]
	v_or_b32_e32 v26, 2, v20
	v_ashrrev_i32_e32 v27, 31, v26
	v_lshlrev_b64 v[30:31], 11, v[26:27]
	v_or_b32_e32 v26, 1, v20
	v_ashrrev_i32_e32 v27, 31, v26
	v_lshlrev_b64 v[36:37], 11, v[26:27]
	v_ashrrev_i32_e32 v21, 31, v20
	v_or_b32_e32 v30, v30, v44
	v_or_b32_e32 v36, v36, v44
	v_lshlrev_b64 v[42:43], 11, v[20:21]
	v_lshl_add_u64 v[34:35], s[12:13], 0, v[30:31]
	v_lshl_add_u64 v[38:39], s[12:13], 0, v[36:37]
	v_or_b32_e32 v42, v42, v44
	v_lshl_add_u64 v[44:45], s[12:13], 0, v[42:43]
	global_load_ushort v20, v[28:29], off
	global_load_ushort v21, v[34:35], off
	global_load_ushort v26, v[38:39], off
	global_load_ushort v27, v[44:45], off
	v_lshl_add_u64 v[34:35], s[10:11], 0, v[30:31]
	v_lshl_add_u64 v[36:37], s[10:11], 0, v[36:37]
	v_lshl_add_u64 v[38:39], s[10:11], 0, v[42:43]
	global_load_ushort v28, v[32:33], off
	global_load_ushort v29, v[34:35], off
	global_load_ushort v30, v[36:37], off
	global_load_ushort v31, v[38:39], off
	s_movk_i32 s2, 0xff
	v_cmp_lt_u32_e64 s[4:5], s2, v209
	s_movk_i32 s2, 0x17f
	v_lshl_add_u32 v43, v40, 2, 0
	v_cmp_lt_u32_e64 s[6:7], s2, v209
	s_movk_i32 s2, 0x1ff
	v_mul_u32_u24_e32 v32, 0x8c, v40
	v_lshlrev_b32_e32 v33, 1, v41
	v_readlane_b32 s14, v245, 21
	v_cmp_lt_u32_e64 s[8:9], s2, v209
; #define LAS __attribute__((address_space(3)))
; __device__ __forceinline__ unsigned pk2_rne(float lo, float hi) { const f32x2_t f = {lo, hi}; return __builtin_bit_cast(unsigned, __builtin_convertvector(f, bf16x2_t)); }
; #define MFMA32(a, b, c) __builtin_amdgcn_mfma_f32_32x32x16_bf16((a), (b), (c), 0, 0, 0)
; __device__ __forceinline__ void hgrn_a_compute(Ctx& X, int u, const RawA& R) {
;     ...
;     const int vt = w >> 1, kt2 = 2 * (w & 1);
;     f32x16 acc[2];
; #pragma unroll
;     for (int e = 0; e < 2; ++e)
; #pragma unroll
;         for (int i = 0; i < 16; ++i) acc[e][i] = 0.f;
; #pragma unroll
;     for (int ks = 0; ks < 4; ++ks) {
;         const bf16x8 bfr = *(const LAS bf16x8*)(VT + (32 * vt + r) * 72 + 16 * ks + 8 * h);
; #pragma unroll
;         for (int e = 0; e < 2; ++e) { const bf16x8 af = *(const LAS bf16x8*)(KT + (32 * (kt2 + e) + r) * 72 + 16 * ks + 8 * h); acc[e] = MFMA32(af, bfr, acc[e]); }
;     }
;     bf16_t* P = (bf16_t*)X.out + (size_t)u * 16384;
; #pragma unroll
;     for (int e = 0; e < 2; ++e)
; #pragma unroll
;         for (int g = 0; g < 4; ++g) {
;             { u32x2 pw; pw.x = pk2_rne(acc[e][4 * g], acc[e][4 * g + 1]); pw.y = pk2_rne(acc[e][4 * g + 2], acc[e][4 * g + 3]);
;               *(u32x2*)(P + (32 * vt + r) * 128 + 32 * (kt2 + e) + 8 * g + 4 * h) = pw; }
;         }
	v_add3_u32 v44, v43, v32, v33
	v_lshrrev_b32_e32 v32, 5, v208
	v_and_b32_e32 v34, 31, v209
	s_lshr_b32 s2, s14, 7
	s_and_b32 s16, s14, 64
	v_lshl_or_b32 v33, s2, 5, v34
	v_lshl_add_u32 v46, v32, 4, 0
	s_movk_i32 s14, 0x90
	v_lshlrev_b32_e32 v38, 4, v32
	v_mad_u64_u32 v[32:33], s[14:15], v33, s14, v[46:47]
	v_or_b32_e32 v33, s16, v34
	v_mul_u32_u24_e32 v45, 0x90, v33
	v_or_b32_e32 v33, 32, v33
	v_mul_u32_u24_e32 v47, 0x90, v33
	v_lshlrev_b32_e32 v33, 7, v34
	v_lshl_or_b32 v34, s2, 12, v33
	v_ashrrev_i32_e32 v35, 31, v34
	v_lshl_add_u64 v[34:35], v[34:35], 1, s[88:89]
	v_mov_b32_e32 v39, 0
	v_readlane_b32 s21, v245, 1
	s_mov_b32 s3, 0
	v_lshl_add_u64 v[34:35], v[34:35], 0, v[38:39]
	s_lshl_b32 s2, s16, 1
	v_lshl_add_u64 v[34:35], v[34:35], 0, s[2:3]
	s_add_i32 s2, s20, s94
	s_ashr_i32 s21, s20, 31
	s_lshl_b32 s26, s2, 3
	s_lshl_b32 s27, s2, 7
	s_lshl_b32 s28, s94, 7
	s_ashr_i32 s15, s94, 31
	s_lshl_b64 s[2:3], s[20:21], 9
	s_add_u32 s2, s90, s2
	v_lshlrev_b32_e32 v36, 2, v209
	v_mov_b32_e32 v37, v39
	s_addc_u32 s3, s91, s3
	v_add_u32_e32 v42, 0, v36
	v_lshl_add_u64 v[36:37], s[2:3], 0, v[36:37]
	s_mov_b64 s[2:3], 0x4700000
	s_movk_i32 s0, 0x80
	s_mov_b32 s14, s94
	v_lshl_add_u64 v[36:37], v[36:37], 0, s[2:3]
	s_mov_b32 s2, s20
	v_cmp_gt_u32_e64 s[0:1], s0, v209
	s_lshl_b64 s[16:17], s[14:15], 9
	v_add_u32_e32 v33, v46, v45
	v_add_u32_e32 v45, v46, v47
	s_mov_b64 s[18:19], s[20:21]
	v_writelane_b32 v245, s2, 0
	s_waitcnt vmcnt(0)
	v_mov_b32_e32 v73, v2
	v_mov_b32_e32 v72, v3
	v_mov_b32_e32 v71, v1
	v_mov_b32_e32 v70, v0
	v_mov_b32_e32 v65, v4
	v_mov_b32_e32 v64, v5
	v_mov_b32_e32 v63, v8
	v_mov_b32_e32 v62, v9
	v_mov_b32_e32 v57, v12
	v_mov_b32_e32 v56, v13
	v_mov_b32_e32 v55, v17
	v_mov_b32_e32 v54, v18
	v_mov_b32_e32 v77, v6
	v_mov_b32_e32 v49, v20
	v_mov_b32_e32 v48, v21
	v_mov_b32_e32 v47, v26
	v_mov_b32_e32 v46, v27
	v_mov_b32_e32 v76, v7
	v_mov_b32_e32 v75, v10
	v_mov_b32_e32 v74, v11
	v_mov_b32_e32 v69, v14
	v_mov_b32_e32 v68, v15
	v_mov_b32_e32 v67, v16
	v_mov_b32_e32 v66, v19
	v_mov_b32_e32 v61, v22
	v_mov_b32_e32 v60, v23
	v_mov_b32_e32 v59, v24
	v_mov_b32_e32 v58, v25
	v_mov_b32_e32 v53, v28
	v_mov_b32_e32 v52, v29
	v_mov_b32_e32 v51, v30
	v_mov_b32_e32 v50, v31
	v_writelane_b32 v245, s3, 1
	v_lshrrev_b32_e32 v100, 6, v209
	v_mul_u32_u24_e32 v100, 0x1200, v100
	v_add_u32_e32 v100, 0xa000, v100
	v_and_b32_e32 v101, 31, v209
	v_mul_u32_u24_e32 v101, 0x90, v101
	v_bfe_u32 v102, v209, 5, 1
	v_lshl_add_u32 v101, v102, 3, v101
	v_add_u32_e32 v108, v100, v101
	v_bfe_u32 v101, v209, 3, 3
	v_and_b32_e32 v102, 7, v209
	v_mul_u32_u24_e32 v103, 0x90, v101
	v_lshl_add_u32 v103, v102, 4, v103
	v_add_u32_e32 v109, v100, v103
	v_lshrrev_b32_e32 v103, 7, v209
	v_lshl_add_u32 v103, v103, 5, v101
	v_lshlrev_b32_e32 v103, 8, v103
	v_bfe_u32 v104, v209, 6, 1
	v_lshl_add_u32 v103, v104, 7, v103
	v_lshl_add_u32 v104, v102, 4, v103
	v_add_u32_e32 v104, 0x1000, v104
	v_mov_b32_e32 v105, 0
	v_lshl_add_u64 v[106:107], s[88:89], 0, v[104:105]
	s_branch .LBB0_467
.LBB0_466:
	s_or_b64 exec, exec, s[24:25]
	s_waitcnt lgkmcnt(0)
	s_barrier
	ds_read_b128 v[0:3], v33
	ds_read_b128 v[4:7], v32 offset:18432
	ds_read_b128 v[78:81], v32 offset:18464
	ds_read_b128 v[82:85], v33 offset:32
	s_waitcnt lgkmcnt(2)
	v_mfma_f32_32x32x16_bf16 v[16:31], v[0:3], v[4:7], 0
	ds_read_b128 v[0:3], v45
	ds_read_b128 v[86:89], v45 offset:32
	v_lshlrev_b64 v[38:39], 15, v[38:39]
	v_lshl_add_u64 v[110:111], v[106:107], 0, v[38:39]
	v_lshl_add_u64 v[38:39], v[34:35], 0, v[38:39]
	s_add_i32 s26, s26, s50
	s_add_i32 s27, s27, s28
	s_add_u32 s18, s18, s14
	s_addc_u32 s19, s19, s15
	s_waitcnt lgkmcnt(1)
	v_mfma_f32_32x32x16_bf16 v[0:15], v[0:3], v[4:7], 0
	v_lshl_add_u64 v[36:37], v[36:37], 0, s[16:17]
	s_and_b64 vcc, exec, s[22:23]
	s_mov_b32 s20, s2
	v_mfma_f32_32x32x16_bf16 v[16:31], v[82:85], v[78:81], v[16:31]
	s_waitcnt lgkmcnt(0)
	v_mfma_f32_32x32x16_bf16 v[0:15], v[86:89], v[78:81], v[0:15]
	ds_read_b128 v[78:81], v33 offset:64
	ds_read_b128 v[82:85], v32 offset:18496
	ds_read_b128 v[86:89], v32 offset:18528
	ds_read_b128 v[90:93], v33 offset:96
	s_waitcnt lgkmcnt(2)
	v_mfma_f32_32x32x16_bf16 v[16:31], v[78:81], v[82:85], v[16:31]
	ds_read_b128 v[78:81], v45 offset:64
	ds_read_b128 v[94:97], v45 offset:96
	s_waitcnt lgkmcnt(1)
	v_mfma_f32_32x32x16_bf16 v[0:15], v[78:81], v[82:85], v[0:15]
	v_mfma_f32_32x32x16_bf16 v[16:31], v[90:93], v[86:89], v[16:31]
	s_waitcnt lgkmcnt(0)
	v_mfma_f32_32x32x16_bf16 v[0:15], v[94:97], v[86:89], v[0:15]
	s_nop 9
	v_cvt_pk_bf16_f32 v16, v16, v17
	v_cvt_pk_bf16_f32 v17, v18, v19
	v_cvt_pk_bf16_f32 v18, v20, v21
	v_cvt_pk_bf16_f32 v19, v22, v23
	v_cvt_pk_bf16_f32 v20, v24, v25
	v_cvt_pk_bf16_f32 v21, v26, v27
	v_cvt_pk_bf16_f32 v22, v28, v29
	v_cvt_pk_bf16_f32 v23, v30, v31
	ds_write_b64 v108, v[16:17]
	ds_write_b64 v108, v[18:19] offset:16
	v_cvt_pk_bf16_f32 v0, v0, v1
	v_cvt_pk_bf16_f32 v1, v2, v3
	v_cvt_pk_bf16_f32 v2, v4, v5
	v_cvt_pk_bf16_f32 v3, v6, v7
	ds_write_b64 v108, v[20:21] offset:32
	ds_write_b64 v108, v[22:23] offset:48
	v_cvt_pk_bf16_f32 v4, v8, v9
	v_cvt_pk_bf16_f32 v5, v10, v11
	v_cvt_pk_bf16_f32 v6, v12, v13
	v_cvt_pk_bf16_f32 v7, v14, v15
	ds_write_b64 v108, v[0:1] offset:64
	ds_write_b64 v108, v[2:3] offset:80
	ds_write_b64 v108, v[4:5] offset:96
	ds_write_b64 v108, v[6:7] offset:112
	s_waitcnt lgkmcnt(0)
	ds_read_b128 v[112:115], v109
	ds_read_b128 v[116:119], v109 offset:1152
	ds_read_b128 v[120:123], v109 offset:2304
	ds_read_b128 v[124:127], v109 offset:3456
	v_mov_b32_e32 v128, v110
	v_mov_b32_e32 v129, v111
	s_cmp_eq_u32 s98, 0
	s_cbranch_scc1 .Lha_w0
	s_waitcnt vmcnt(4) lgkmcnt(0)
	s_branch .Lha_w1

; __device__ __forceinline__ void hgrn_a_compute(Ctx& X, int u, const RawA& R) {
;     ...
;     __syncthreads();
; __global__ void __launch_bounds__(512, 2) fwd_mega(Args a) {
;     ...
;             for (int u = blockIdx.x; u < 2048; u += X.G) { RawA nxt = cur; if (u + X.G < 2048) hgrn_a_load(X, u + X.G, nxt); hgrn_a_compute(X, u, cur); cur = nxt; }
.Lha_w1:
	s_mov_b32 s98, 1
	s_nop 1
	v_mov_b32_e32 v2, v73
	v_mov_b32_e32 v3, v72
	v_mov_b32_e32 v1, v71
	v_mov_b32_e32 v0, v70
	v_mov_b32_e32 v4, v65
	v_mov_b32_e32 v5, v64
	v_mov_b32_e32 v8, v63
	v_mov_b32_e32 v9, v62
	v_mov_b32_e32 v12, v57
	v_mov_b32_e32 v13, v56
	v_mov_b32_e32 v17, v55
	v_mov_b32_e32 v18, v54
	v_mov_b32_e32 v20, v49
	v_mov_b32_e32 v21, v48
	v_mov_b32_e32 v26, v47
	v_mov_b32_e32 v27, v46
	v_mov_b32_e32 v6, v77
	v_mov_b32_e32 v7, v76
	v_mov_b32_e32 v10, v75
	v_mov_b32_e32 v11, v74
	v_mov_b32_e32 v14, v69
	v_mov_b32_e32 v15, v68
	v_mov_b32_e32 v16, v67
	v_mov_b32_e32 v31, v50
	v_mov_b32_e32 v30, v51
	v_mov_b32_e32 v29, v52
	v_mov_b32_e32 v28, v53
	v_mov_b32_e32 v25, v58
	v_mov_b32_e32 v24, v59
	v_mov_b32_e32 v23, v60
	v_mov_b32_e32 v22, v61
	v_mov_b32_e32 v19, v66
	s_barrier
	s_cbranch_vccnz .LBB0_471

; __device__ __forceinline__ unsigned pk2_rne(float lo, float hi) { const f32x2_t f = {lo, hi}; return __builtin_bit_cast(unsigned, __builtin_convertvector(f, bf16x2_t)); }
; __device__ __forceinline__ float bf2f(unsigned short b) { return __uint_as_float(((unsigned)b) << 16); }
; __device__ __forceinline__ void hgrn_a_compute(Ctx& X, int u, const RawA& R) {
;     ...
;     float lf[16], b[16]; float run = 0.f;
; #pragma unroll
;     for (int i = 0; i < 16; ++i) { lf[i] = bf2f(R.lf[i]); run += lf[i]; b[i] = run; }
;     SEG[seg * 128 + k] = run;
;     __syncthreads();
;     float off = 0.f, tot = 0.f;
; #pragma unroll
;     for (int s = 0; s < 4; ++s) { const float v = SEG[s * 128 + k]; tot += v; off += (s < seg) ? v : 0.f; }
;     {
;         unsigned pk[8], pv[8];
; #pragma unroll
;         for (int i = 0; i < 8; ++i) {
;             const float k0 = (1.f - __expf(lf[2 * i])) * __expf(tot - (off + b[2 * i])), k1 = (1.f - __expf(lf[2 * i + 1])) * __expf(tot - (off + b[2 * i + 1]));
;             pk[i] = pk2_rne(k0, k1); pv[i] = (unsigned)R.vv[2 * i] | ((unsigned)R.vv[2 * i + 1] << 16);
.LBB0_469:
	v_lshlrev_b32_e32 v31, 16, v31
	v_add_f32_e32 v38, 0, v31
	v_lshlrev_b32_e32 v30, 16, v30
	v_lshlrev_b32_e32 v29, 16, v29
	v_lshlrev_b32_e32 v28, 16, v28
	v_lshlrev_b32_e32 v95, 16, v10
	v_mul_f32_e32 v10, 0x3fb8aa3b, v31
	v_lshlrev_b32_e32 v31, 16, v6
	v_lshlrev_b32_e32 v6, 16, v26
	v_add_f32_e32 v78, v38, v30
	v_lshlrev_b32_e32 v91, 16, v14
	v_lshlrev_b32_e32 v93, 16, v11
	v_mul_f32_e32 v11, 0x3fb8aa3b, v30
	v_lshlrev_b32_e32 v30, 16, v7
	v_or_b32_sdwa v14, v6, v27 dst_sel:DWORD dst_unused:UNUSED_PAD src0_sel:DWORD src1_sel:WORD_0
	v_mul_f32_e32 v6, 0x3fb8aa3b, v29
	v_mul_f32_e32 v7, 0x3fb8aa3b, v28
	v_exp_f32_e32 v6, v6
	v_exp_f32_e32 v7, v7
	s_cmp_eq_u32 s98, 0
	s_cbranch_scc1 .Lha_skip0
	global_store_dwordx4 v[128:129], v[112:115], off offset:-4096
.Lha_skip0:
	v_add_f32_e32 v79, v78, v29
	v_add_f32_e32 v80, v79, v28
	v_lshlrev_b32_e32 v25, 16, v25
	v_add_f32_e32 v81, v80, v25
	v_lshlrev_b32_e32 v24, 16, v24
	v_lshlrev_b32_e32 v89, 16, v15
	v_mul_f32_e32 v15, 0x3fb8aa3b, v25
	v_add_f32_e32 v82, v81, v24
	v_lshlrev_b32_e32 v84, 16, v22
	v_exp_f32_e32 v22, v15
	v_mul_f32_e32 v15, 0x3fb8aa3b, v24
	v_pk_add_f32 v[24:25], v[6:7], 1.0 op_sel_hi:[1,0] neg_lo:[1,0] neg_hi:[1,0]
	v_lshlrev_b32_e32 v6, 16, v20
	v_lshlrev_b32_e32 v39, 16, v23
	v_exp_f32_e32 v23, v15
	v_or_b32_sdwa v15, v6, v21 dst_sel:DWORD dst_unused:UNUSED_PAD src0_sel:DWORD src1_sel:WORD_0
	v_lshlrev_b32_e32 v6, 16, v17
	v_lshlrev_b32_e32 v87, 16, v16
	v_or_b32_sdwa v16, v6, v18 dst_sel:DWORD dst_unused:UNUSED_PAD src0_sel:DWORD src1_sel:WORD_0
	v_mul_f32_e32 v6, 0x3fb8aa3b, v39
	v_mul_f32_e32 v7, 0x3fb8aa3b, v84
	v_exp_f32_e32 v6, v6
	v_exp_f32_e32 v7, v7
	v_add_f32_e32 v83, v82, v39
	v_lshlrev_b32_e32 v19, 16, v19
	v_add_f32_e32 v85, v83, v84
	v_mul_f32_e32 v17, 0x3fb8aa3b, v19
	v_add_f32_e32 v86, v85, v19
	v_pk_add_f32 v[20:21], v[22:23], 1.0 op_sel_hi:[1,0] neg_lo:[1,0] neg_hi:[1,0]
	v_exp_f32_e32 v18, v17
	v_mul_f32_e32 v17, 0x3fb8aa3b, v87
	v_pk_add_f32 v[22:23], v[6:7], 1.0 op_sel_hi:[1,0] neg_lo:[1,0] neg_hi:[1,0]
	v_lshlrev_b32_e32 v6, 16, v12
	v_mul_f32_e32 v7, 0x3fb8aa3b, v89
	v_add_f32_e32 v88, v86, v87
	v_exp_f32_e32 v19, v17
	v_or_b32_sdwa v17, v6, v13 dst_sel:DWORD dst_unused:UNUSED_PAD src0_sel:DWORD src1_sel:WORD_0
	v_lshlrev_b32_e32 v6, 16, v8
	v_exp_f32_e32 v8, v7
	v_mul_f32_e32 v7, 0x3fb8aa3b, v91
	v_add_f32_e32 v90, v88, v89
	v_or_b32_sdwa v6, v6, v9 dst_sel:DWORD dst_unused:UNUSED_PAD src0_sel:DWORD src1_sel:WORD_0
	v_exp_f32_e32 v9, v7
	v_mul_f32_e32 v7, 0x3fb8aa3b, v93
	v_add_f32_e32 v92, v90, v91
	v_exp_f32_e32 v12, v7
	v_mul_f32_e32 v7, 0x3fb8aa3b, v95
	v_add_f32_e32 v94, v92, v93
	v_exp_f32_e32 v13, v7
	v_add_f32_e32 v96, v94, v95
	v_add_f32_e32 v97, v96, v30
	v_pk_add_f32 v[26:27], v[8:9], 1.0 op_sel_hi:[1,0] neg_lo:[1,0] neg_hi:[1,0]
	v_lshlrev_b32_e32 v4, 16, v4
	v_lshlrev_b32_e32 v8, 16, v1
	v_add_f32_e32 v1, v97, v31
	v_or_b32_sdwa v7, v4, v5 dst_sel:DWORD dst_unused:UNUSED_PAD src0_sel:DWORD src1_sel:WORD_0
	v_pk_add_f32 v[4:5], v[12:13], 1.0 op_sel_hi:[1,0] neg_lo:[1,0] neg_hi:[1,0]
	ds_write_b32 v42, v1 offset:36864
	s_waitcnt lgkmcnt(0)
	s_barrier
	ds_read2st64_b32 v[12:13], v43 offset0:144 offset1:146
	v_or_b32_sdwa v8, v8, v0 dst_sel:DWORD dst_unused:UNUSED_PAD src0_sel:DWORD src1_sel:WORD_0
	v_mul_f32_e32 v0, 0x3fb8aa3b, v30
	v_mul_f32_e32 v9, 0x3fb8aa3b, v31
	ds_read2st64_b32 v[30:31], v43 offset0:148 offset1:150
	v_exp_f32_e32 v28, v0
	s_waitcnt lgkmcnt(1)
	v_add_f32_e32 v0, 0, v12
	v_cndmask_b32_e64 v12, v0, 0, s[0:1]
	s_cmp_eq_u32 s98, 0
	s_cbranch_scc1 .Lha_skip1
	global_store_dwordx4 v[128:129], v[116:119], off offset:-2048
; #define LAS __attribute__((address_space(3)))
; __device__ __forceinline__ unsigned pk2_rne(float lo, float hi) { const f32x2_t f = {lo, hi}; return __builtin_bit_cast(unsigned, __builtin_convertvector(f, bf16x2_t)); }
; __device__ __forceinline__ float bf2f(unsigned short b) { return __uint_as_float(((unsigned)b) << 16); }
; __device__ __forceinline__ void hgrn_a_compute(Ctx& X, int u, const RawA& R) {
;     ...
;     for (int i = 0; i < 16; ++i) { lf[i] = bf2f(R.lf[i]); run += lf[i]; b[i] = run; }
;     SEG[seg * 128 + k] = run;
;     __syncthreads();
;     float off = 0.f, tot = 0.f;
; #pragma unroll
;     for (int s = 0; s < 4; ++s) { const float v = SEG[s * 128 + k]; tot += v; off += (s < seg) ? v : 0.f; }
;     {
;         unsigned pk[8], pv[8];
; #pragma unroll
;         for (int i = 0; i < 8; ++i) {
;             const float k0 = (1.f - __expf(lf[2 * i])) * __expf(tot - (off + b[2 * i])), k1 = (1.f - __expf(lf[2 * i + 1])) * __expf(tot - (off + b[2 * i + 1]));
;             pk[i] = pk2_rne(k0, k1); pv[i] = (unsigned)R.vv[2 * i] | ((unsigned)R.vv[2 * i + 1] << 16);
;         }
;         *(LAS u32x4*)(KT + k * 72 + 16 * seg) = (u32x4){pk[0], pk[1], pk[2], pk[3]}; *(LAS u32x4*)(KT + k * 72 + 16 * seg + 8) = (u32x4){pk[4], pk[5], pk[6], pk[7]};
;         *(LAS u32x4*)(VT + k * 72 + 16 * seg) = (u32x4){pv[0], pv[1], pv[2], pv[3]}; *(LAS u32x4*)(VT + k * 72 + 16 * seg + 8) = (u32x4){pv[4], pv[5], pv[6], pv[7]};
;     }
;     if (seg == 0) ((float*)(X.ws + WS_DBUF))[(size_t)u * 128 + k] = __expf(tot);
;     ...
;     bf16_t* P = (bf16_t*)X.out + (size_t)u * 16384;
; #pragma unroll
;     for (int e = 0; e < 2; ++e)
; #pragma unroll
;         for (int g = 0; g < 4; ++g) {
;             { u32x2 pw; pw.x = pk2_rne(acc[e][4 * g], acc[e][4 * g + 1]); pw.y = pk2_rne(acc[e][4 * g + 2], acc[e][4 * g + 3]);
;               *(u32x2*)(P + (32 * vt + r) * 128 + 32 * (kt2 + e) + 8 * g + 4 * h) = pw; }
.Lha_skip1:
	v_add_f32_e32 v0, v0, v13
	v_cndmask_b32_e64 v13, 0, v13, s[4:5]
	v_add_f32_e32 v12, v12, v13
	s_waitcnt lgkmcnt(0)
	v_cndmask_b32_e64 v13, 0, v30, s[6:7]
	v_add_f32_e32 v12, v12, v13
	v_cndmask_b32_e64 v13, 0, v31, s[8:9]
	v_add_f32_e32 v39, v12, v13
	v_add_f32_e32 v0, v0, v30
	v_add_f32_e32 v12, v38, v39
	v_mov_b32_e32 v38, v31
	v_pk_add_f32 v[0:1], v[0:1], v[38:39]
	v_add_f32_e32 v29, v79, v39
	v_sub_f32_e32 v29, v0, v29
	v_mul_f32_e32 v29, 0x3fb8aa3b, v29
	v_add_f32_e32 v13, v78, v39
	v_exp_f32_e32 v30, v29
	v_add_f32_e32 v29, v80, v39
	v_sub_f32_e32 v12, v0, v12
	v_sub_f32_e32 v13, v0, v13
	v_sub_f32_e32 v29, v0, v29
	v_exp_f32_e32 v10, v10
	v_exp_f32_e32 v11, v11
	v_mul_f32_e32 v12, 0x3fb8aa3b, v12
	v_mul_f32_e32 v13, 0x3fb8aa3b, v13
	v_mul_f32_e32 v29, 0x3fb8aa3b, v29
	v_exp_f32_e32 v12, v12
	v_exp_f32_e32 v13, v13
	v_exp_f32_e32 v31, v29
	v_exp_f32_e32 v29, v9
	v_add_f32_e32 v9, v81, v39
	v_sub_f32_e32 v9, v0, v9
	v_pk_add_f32 v[10:11], v[10:11], 1.0 op_sel_hi:[1,0] neg_lo:[1,0] neg_hi:[1,0]
	v_mul_f32_e32 v9, 0x3fb8aa3b, v9
	v_pk_mul_f32 v[10:11], v[10:11], v[12:13]
	v_pk_mul_f32 v[12:13], v[24:25], v[30:31]
	v_exp_f32_e32 v24, v9
	v_add_f32_e32 v9, v82, v39
	v_sub_f32_e32 v9, v0, v9
	v_mul_f32_e32 v9, 0x3fb8aa3b, v9
	v_exp_f32_e32 v25, v9
	v_add_f32_e32 v9, v83, v39
	v_sub_f32_e32 v9, v0, v9
	v_mul_f32_e32 v9, 0x3fb8aa3b, v9
	v_exp_f32_e32 v30, v9
	v_add_f32_e32 v9, v85, v39
	s_cmp_eq_u32 s98, 0
	s_cbranch_scc1 .Lha_skip2
	global_store_dwordx4 v[128:129], v[120:123], off
.Lha_skip2:
	v_sub_f32_e32 v9, v0, v9
	v_mul_f32_e32 v9, 0x3fb8aa3b, v9
	v_exp_f32_e32 v31, v9
	v_add_f32_e32 v9, v86, v39
	v_sub_f32_e32 v9, v0, v9
	v_mul_f32_e32 v9, 0x3fb8aa3b, v9
	v_cvt_pk_bf16_f32 v10, v10, v11
	v_cvt_pk_bf16_f32 v11, v12, v13
	v_pk_mul_f32 v[12:13], v[20:21], v[24:25]
	v_pk_mul_f32 v[20:21], v[22:23], v[30:31]
	v_exp_f32_e32 v22, v9
	v_add_f32_e32 v9, v88, v39
	v_sub_f32_e32 v9, v0, v9
	v_mul_f32_e32 v9, 0x3fb8aa3b, v9
	v_exp_f32_e32 v23, v9
	v_add_f32_e32 v9, v90, v39
	v_sub_f32_e32 v9, v0, v9
	v_mul_f32_e32 v9, 0x3fb8aa3b, v9
	v_exp_f32_e32 v24, v9
	v_add_f32_e32 v9, v92, v39
	v_sub_f32_e32 v9, v0, v9
	v_mul_f32_e32 v9, 0x3fb8aa3b, v9
	v_exp_f32_e32 v25, v9
	v_add_f32_e32 v9, v94, v39
	v_pk_add_f32 v[18:19], v[18:19], 1.0 op_sel_hi:[1,0] neg_lo:[1,0] neg_hi:[1,0]
	v_sub_f32_e32 v9, v0, v9
	v_cvt_pk_bf16_f32 v12, v12, v13
	v_cvt_pk_bf16_f32 v13, v20, v21
	v_pk_mul_f32 v[18:19], v[18:19], v[22:23]
	v_pk_mul_f32 v[20:21], v[26:27], v[24:25]
	v_mul_f32_e32 v9, 0x3fb8aa3b, v9
	v_cvt_pk_bf16_f32 v18, v18, v19
	v_cvt_pk_bf16_f32 v19, v20, v21
	v_exp_f32_e32 v20, v9
	v_add_f32_e32 v9, v96, v39
	v_sub_f32_e32 v9, v0, v9
	v_mul_f32_e32 v9, 0x3fb8aa3b, v9
	v_exp_f32_e32 v21, v9
	v_add_f32_e32 v9, v97, v39
	v_sub_f32_e32 v9, v0, v9
	v_sub_f32_e32 v1, v0, v1
	v_mul_f32_e32 v9, 0x3fb8aa3b, v9
	v_mul_f32_e32 v1, 0x3fb8aa3b, v1
	v_exp_f32_e32 v22, v9
	v_exp_f32_e32 v23, v1
	v_pk_mul_f32 v[4:5], v[4:5], v[20:21]
	v_lshlrev_b32_e32 v1, 16, v2
	v_cvt_pk_bf16_f32 v20, v4, v5
	v_pk_add_f32 v[4:5], v[28:29], 1.0 op_sel_hi:[1,0] neg_lo:[1,0] neg_hi:[1,0]
	s_cmp_eq_u32 s98, 0
	s_cbranch_scc1 .Lha_skip3
	global_store_dwordx4 v[128:129], v[124:127], off offset:2048
.Lha_skip3:
	v_mov_b64_e32 v[38:39], s[18:19]
	v_pk_mul_f32 v[4:5], v[4:5], v[22:23]
	v_or_b32_sdwa v9, v1, v3 dst_sel:DWORD dst_unused:UNUSED_PAD src0_sel:DWORD src1_sel:WORD_0
	v_cvt_pk_bf16_f32 v21, v4, v5
	ds_write_b128 v44, v[10:13]
	ds_write_b128 v44, v[18:21] offset:16
	ds_write_b128 v44, v[14:17] offset:18432
	ds_write_b128 v44, v[6:9] offset:18448
	s_and_saveexec_b64 s[24:25], s[0:1]
	s_cbranch_execz .LBB0_466
	v_mul_f32_e32 v0, 0x3fb8aa3b, v0
	v_exp_f32_e32 v0, v0
	s_ashr_i32 s21, s20, 31
	v_mov_b64_e32 v[38:39], s[20:21]
	global_store_dword v[36:37], v0, off
	s_branch .LBB0_466
.LBB0_471:
	s_cmp_eq_u32 s98, 0
	s_cbranch_scc1 .Lha_noflush
	global_store_dwordx4 v[128:129], v[112:115], off offset:-4096
	global_store_dwordx4 v[128:129], v[116:119], off offset:-2048
	global_store_dwordx4 v[128:129], v[120:123], off
	global_store_dwordx4 v[128:129], v[124:127], off offset:2048
